# acquires also dropped behind barriers 5 and 7 (every overlay pair keeps an acquire at barrier 4 or 6 between the last read of the old buffer and the first read of the new one)
# baseline (speedup 1.0000x reference)
.LBB0_711:
	s_or_b64 exec, exec, s[6:7]
	v_cvt_f32_u32_e32 v4, v2
	s_waitcnt vmcnt(0)
	v_readfirstlane_b32 s2, v3
	v_sub_u32_e32 v3, 0, v2
	v_rcp_iflag_f32_e32 v4, v4
	v_add_u32_e32 v5, s2, v1
	v_mul_f32_e32 v4, 0x4f7ffffe, v4
	v_cvt_u32_f32_e32 v4, v4
	v_mul_lo_u32 v1, v3, v4
	v_mul_hi_u32 v1, v4, v1
	v_add_u32_e32 v1, v4, v1
	v_mul_hi_u32 v1, v5, v1
	v_mul_lo_u32 v3, v1, v2
	v_sub_u32_e32 v3, v5, v3
	v_add_u32_e32 v4, 1, v1
	v_cmp_ge_u32_e32 vcc, v3, v2
	s_nop 1
	v_cndmask_b32_e32 v1, v1, v4, vcc
	v_sub_u32_e32 v4, v3, v2
	v_cndmask_b32_e32 v3, v3, v4, vcc
	v_add_u32_e32 v4, 1, v1
	v_cmp_ge_u32_e32 vcc, v3, v2
	v_add_u32_e32 v3, 1, v5
	s_nop 0
	v_cndmask_b32_e32 v1, v1, v4, vcc
	v_mul_lo_u32 v4, v2, v1
	v_add_u32_e32 v2, v4, v2
	v_cmp_ne_u32_e32 vcc, v3, v2
	s_and_saveexec_b64 s[6:7], vcc
	s_xor_b64 s[6:7], exec, s[6:7]
	s_cbranch_execz .LBB0_725
	s_waitcnt lgkmcnt(0)
	v_mov_b32_e32 v0, 0
	s_nop 0
	global_load_dword v2, v0, s[34:35] sc1
	s_waitcnt vmcnt(0)
	v_cmp_eq_u32_e32 vcc, v2, v1
	s_and_saveexec_b64 s[10:11], vcc
	s_cbranch_execz .LBB0_724
	s_mov_b32 s2, 1
	s_mov_b64 s[12:13], 0
	s_branch .LBB0_715

.LBB0_725:
	s_andn2_saveexec_b64 s[6:7], s[6:7]
	s_cbranch_execz .LBB0_745
	s_mov_b64 s[10:11], exec
	buffer_wbl2 sc1
	s_waitcnt vmcnt(0) lgkmcnt(0)
	s_nop 0
	v_add_u32_e32 v4, 1, v1
	v_mul_lo_u32 v4, v4, v0
	v_readlane_b32 s10, v254, 50
	v_readlane_b32 s11, v254, 51
	v_mov_b32_e32 v2, 0
	v_mov_b32_e32 v3, 1
	s_mov_b32 s2, 0
	s_nop 4
	global_atomic_add v2, v3, s[10:11]

.LBB0_886:
	s_or_b64 exec, exec, s[4:5]
	v_cvt_f32_u32_e32 v4, v2
	s_waitcnt vmcnt(0)
	v_readfirstlane_b32 s2, v3
	v_sub_u32_e32 v3, 0, v2
	v_rcp_iflag_f32_e32 v4, v4
	v_add_u32_e32 v5, s2, v1
	v_mul_f32_e32 v4, 0x4f7ffffe, v4
	v_cvt_u32_f32_e32 v4, v4
	v_mul_lo_u32 v1, v3, v4
	v_mul_hi_u32 v1, v4, v1
	v_add_u32_e32 v1, v4, v1
	v_mul_hi_u32 v1, v5, v1
	v_mul_lo_u32 v3, v1, v2
	v_sub_u32_e32 v3, v5, v3
	v_add_u32_e32 v4, 1, v1
	v_cmp_ge_u32_e32 vcc, v3, v2
	s_nop 1
	v_cndmask_b32_e32 v1, v1, v4, vcc
	v_sub_u32_e32 v4, v3, v2
	v_cndmask_b32_e32 v3, v3, v4, vcc
	v_add_u32_e32 v4, 1, v1
	v_cmp_ge_u32_e32 vcc, v3, v2
	v_add_u32_e32 v3, 1, v5
	s_nop 0
	v_cndmask_b32_e32 v1, v1, v4, vcc
	v_mul_lo_u32 v4, v2, v1
	v_add_u32_e32 v2, v4, v2
	v_cmp_ne_u32_e32 vcc, v3, v2
	s_and_saveexec_b64 s[4:5], vcc
	s_xor_b64 s[4:5], exec, s[4:5]
	s_cbranch_execz .LBB0_900
	s_waitcnt lgkmcnt(0)
	v_mov_b32_e32 v0, 0
	s_nop 0
	global_load_dword v2, v0, s[34:35] sc1
	s_waitcnt vmcnt(0)
	v_cmp_eq_u32_e32 vcc, v2, v1
	s_and_saveexec_b64 s[6:7], vcc
	s_cbranch_execz .LBB0_899
	s_mov_b32 s2, 1
	s_mov_b64 s[10:11], 0
	s_branch .LBB0_890

.LBB0_900:
	s_andn2_saveexec_b64 s[4:5], s[4:5]
	s_cbranch_execz .LBB0_920
	s_mov_b64 s[4:5], exec
	buffer_wbl2 sc1
	s_waitcnt vmcnt(0) lgkmcnt(0)
	s_nop 0
	v_add_u32_e32 v4, 1, v1
	v_mul_lo_u32 v4, v4, v0
	v_readlane_b32 s4, v254, 50
	v_readlane_b32 s5, v254, 51
	v_mov_b32_e32 v2, 0
	v_mov_b32_e32 v3, 1
	s_mov_b32 s2, 0
	s_nop 4
	global_atomic_add v2, v3, s[4:5]
